# v026 + decode units: z-gate tile cache-touch at the step-loop exit
# speedup vs baseline: 1.0174x; 1.0161x over previous
; #define LAS __attribute__((address_space(3)))
; #define CACHE_K IN_(2)
; #define CACHE_V IN_(3)
; #define STATE_HGRN IN_(4)
; DI void decode_unit(Ctx A_, LAS unsigned char* lds, int b, int h, float lam, int wave, int lane, int tid) {
;     ...
;     LAS float* wsf = (LAS float*)(lds + WSF_OFF) + wave * 128;
;     const float* Kc = CACHE_K + ((size_t)b * PAST * 8 + h) * 128; const float* Vc = CACHE_V + ((size_t)b * PAST * 8 + h) * 128;
;     const size_t rowq = (size_t)MP + b * DS;
;     v4f kx[8], vx[8];
;     const unsigned voff = (unsigned)((tid >> 5) * 1024 + (tid & 31) * 4);
;     ...
;     DA_LOAD(0);
;     const int c4_ = tid & 31, kk_ = tid >> 5;
;     LAS unsigned char* kw = lds + (c4_ >> 1) * CS + kk_ * 16 + (c4_ & 1) * 8;
;     LAS unsigned char* vw = lds + VOFF + (c4_ >> 3) * PS + kk_ * 64 + (c4_ & 7) * 8;
;     bf16x8 qr[4];
;     { const bf16* Qg = P + (rowq + (r & 15)) * PLD + C_QA + h * 128 + mp * 64 + hh * 8;
; #pragma unroll
;       for (int d0 = 0; d0 < 4; ++d0) { const v4u w = *(const v4u*)(Qg + d0 * 16); const v4u z = {0u, 0u, 0u, 0u}; qr[d0] = __builtin_bit_cast(bf16x8, r < 16 ? w : z); } }
;     f32x16 o[4];
; #pragma unroll
;     for (int nb = 0; nb < 4; ++nb)
; #pragma unroll
;         for (int i = 0; i < 16; ++i) o[nb][i] = 0.f;
;     float m = -INFINITY, l = 0.f;
;     const int g16 = (lane >> 4) & 1, p4 = lane & 3, q4 = (lane & 15) >> 2;
; __global__ void __launch_bounds__(512, 2) fwd(Args args) {
;     ...
;         bool had_chain = false;
;         { PROBE_T0(21)
; #pragma unroll 1
;         for (;;) { int id; Q_NEXT(0, id); if (id >= 64 + 256) break; had_chain = had_chain || id < 64; const int tid = tid_now(), lane = tid & 63;
;             const bool pr = id < 64; const int sidx = id - 64;
;             hg::hgrn_unit(A_, lds, pr ? (id >> 3) * SEQ : MP + (sidx >> 3) * DS, pr ? 64 : DS, pr ? SEQ / 64 : 1, id & 7, pr ? (const float*)nullptr : STATE_HGRN + (size_t)sidx * 16384,
;                           pr ? OUT_ + O_HP + (size_t)id * 16384 : OUT_ + O_HS + (size_t)sidx * 16384, wave, lane, tid); }
;         PROBE_T1(21) }
;         if (!had_chain && (blockIdx.x & 1)) {
; #pragma unroll 1
;             for (;;) { int id; Q_NEXT(1, id); if (id >= 256) break; const int tid = tid_now(), lane = tid & 63; da::decode_unit(A_, lds, id >> 3, id & 7, lam, wave, lane, tid); }
.LBB0_825:
	s_or_b64 exec, exec, s[4:5]
	s_lshl_b32 s2, s2, 2
	s_add_i32 s2, s2, 0
	s_add_i32 s2, s2, 0x20040
	v_mov_b32_e32 v2, s2
	s_waitcnt lgkmcnt(0)
	s_barrier
	ds_read_b32 v2, v2
	s_mov_b64 s[4:5], -1
	s_waitcnt lgkmcnt(0)
	v_readfirstlane_b32 s2, v2
	s_mov_b32 s101, s2
	s_cmpk_gt_i32 s2, 0xff
	s_cbranch_scc1 .LBB0_820
	s_ashr_i32 s4, s2, 3
	s_lshl_b32 s2, s2, 7
	s_ashr_i32 s5, s4, 31
	s_and_b32 s60, s2, 0x380
	s_lshl_b64 s[6:7], s[4:5], 24
	s_lshl_b32 s2, s60, 2
	v_readlane_b32 s64, v254, 2
	v_mov_b32 v22, v0
	s_or_b32 s2, s6, s2
	v_and_b32_e32 v164, 31, v22
	v_readlane_b32 s68, v254, 6
	v_readlane_b32 s69, v254, 7
	s_add_u32 s8, s68, s2
	v_ashrrev_i32_e32 v23, 5, v22
	v_lshlrev_b32_e32 v180, 2, v164
	v_readlane_b32 s70, v254, 8
	s_addc_u32 s9, s69, s7
	v_lshl_or_b32 v162, v23, 10, v180
	v_readlane_b32 s71, v254, 9
	s_add_u32 s6, s70, s2
	v_lshlrev_b64 v[2:3], 2, v[162:163]
	s_addc_u32 s7, s71, s7
	v_lshl_add_u64 v[166:167], s[8:9], 0, v[2:3]
	v_lshl_add_u64 v[168:169], s[6:7], 0, v[2:3]
	v_add_co_u32_e32 v2, vcc, s26, v166
	global_load_dwordx4 v[82:85], v[166:167], off nt
	global_load_dwordx4 v[86:89], v[168:169], off nt
	v_addc_co_u32_e32 v3, vcc, 0, v167, vcc
	global_load_dwordx4 v[90:93], v[2:3], off nt
	v_add_co_u32_e32 v2, vcc, s26, v168
	s_lshl_b32 s2, s4, 4
	s_nop 0
	v_addc_co_u32_e32 v3, vcc, 0, v169, vcc
	global_load_dwordx4 v[94:97], v[2:3], off nt
	v_add_co_u32_e32 v2, vcc, s46, v166
	s_ashr_i32 s4, s2, 31
	s_nop 0
	v_addc_co_u32_e32 v3, vcc, 0, v167, vcc
	global_load_dwordx4 v[98:101], v[2:3], off nt
	v_add_co_u32_e32 v2, vcc, s46, v168
	s_add_u32 s61, s2, 0x8000
	s_nop 0
	v_addc_co_u32_e32 v3, vcc, 0, v169, vcc
	global_load_dwordx4 v[102:105], v[2:3], off nt
	v_add_co_u32_e32 v2, vcc, s47, v166
	s_addc_u32 s59, s4, 0
	s_nop 0
	v_addc_co_u32_e32 v3, vcc, 0, v167, vcc
	global_load_dwordx4 v[106:109], v[2:3], off nt
	v_add_co_u32_e32 v2, vcc, s47, v168
	v_readlane_b32 s4, v255, 9
	s_nop 0
	v_addc_co_u32_e32 v3, vcc, 0, v169, vcc
	global_load_dwordx4 v[110:113], v[2:3], off nt
	v_add_co_u32_e32 v2, vcc, s48, v166
	v_and_b32_e32 v24, 15, v22
	s_nop 0
	v_addc_co_u32_e32 v3, vcc, 0, v167, vcc
	global_load_dwordx4 v[114:117], v[2:3], off nt
	v_add_co_u32_e32 v2, vcc, s48, v168
	v_readlane_b32 s5, v255, 10
	s_nop 0
	v_addc_co_u32_e32 v3, vcc, 0, v169, vcc
	global_load_dwordx4 v[118:121], v[2:3], off nt
	v_or_b32_e32 v2, s61, v24
	v_mov_b64_e32 v[18:19], s[4:5]
	v_add_co_u32_e32 v10, vcc, s49, v166
	v_mad_u64_u32 v[2:3], s[4:5], v2, s53, v[18:19]
	s_nop 0
	v_addc_co_u32_e32 v11, vcc, 0, v167, vcc
	v_mad_i32_i24 v3, s59, v174, v3
	s_lshl_b32 s2, s60, 1
	v_add_co_u32_e32 v16, vcc, s49, v168
	v_bfe_u32 v179, v22, 5, 1
	v_lshl_add_u64 v[2:3], v[2:3], 0, s[2:3]
	v_addc_co_u32_e32 v17, vcc, 0, v169, vcc
	v_lshl_add_u64 v[2:3], s[10:11], 1, v[2:3]
	v_lshlrev_b32_e32 v162, 4, v179
	v_add_co_u32_e32 v20, vcc, s50, v166
	v_lshl_add_u64 v[14:15], v[2:3], 0, v[162:163]
	s_nop 0
	v_addc_co_u32_e32 v21, vcc, 0, v167, vcc
	global_load_dwordx4 v[2:5], v[14:15], off
	global_load_dwordx4 v[6:9], v[14:15], off offset:32
	global_load_dwordx4 v[130:133], v[10:11], off nt
	s_nop 0
	global_load_dwordx4 v[10:13], v[14:15], off offset:64
	global_load_dwordx4 v[138:141], v[16:17], off nt
	s_nop 0
	global_load_dwordx4 v[14:17], v[14:15], off offset:96
	v_bfe_u32 v26, v22, 3, 2
	global_load_dwordx4 v[146:149], v[20:21], off nt
	v_add_co_u32_e32 v20, vcc, s50, v168
	v_mul_u32_u24_e32 v26, 0x820, v26
	s_nop 0
	v_addc_co_u32_e32 v21, vcc, 0, v169, vcc
	global_load_dwordx4 v[150:153], v[20:21], off nt
	v_add_co_u32_e32 v20, vcc, s51, v166
	s_movk_i32 s6, 0x100
	s_nop 0
	v_addc_co_u32_e32 v21, vcc, 0, v167, vcc
	global_load_dwordx4 v[154:157], v[20:21], off nt
	v_add_co_u32_e32 v20, vcc, s51, v168
	v_lshlrev_b32_e32 v25, 3, v22
	s_nop 0
	v_addc_co_u32_e32 v21, vcc, 0, v169, vcc
	global_load_dwordx4 v[158:161], v[20:21], off nt
	v_bfe_u32 v20, v22, 1, 4
	v_lshlrev_b32_e32 v21, 4, v23
	v_lshlrev_b32_e32 v23, 6, v23
	v_mul_u32_u24_e32 v20, 0x210, v20
	v_add3_u32 v37, 0, v26, v23
	v_bfe_u32 v23, v22, 4, 4
	v_add3_u32 v36, 0, v20, v21
	v_or_b32_e32 v20, s61, v23
	v_mad_u64_u32 v[18:19], s[4:5], v20, s53, v[18:19]
	v_cmp_gt_i32_e32 vcc, s6, v22
	v_mad_i32_i24 v19, s59, v174, v19
	v_mov_b32_e32 v21, v163
	v_cndmask_b32_e32 v20, v175, v176, vcc
	v_lshl_add_u64 v[18:19], v[18:19], 0, v[20:21]
	v_lshlrev_b32_e32 v26, 4, v22
	v_lshl_add_u64 v[18:19], v[18:19], 0, s[2:3]
	v_and_b32_e32 v20, 0xf0, v26
	v_lshl_add_u64 v[170:171], v[18:19], 0, v[20:21]
	v_bfe_u32 v18, v22, 2, 2
	v_mul_u32_u24_e32 v18, 0x820, v18
	v_lshlrev_b32_e32 v19, 6, v23
	v_add3_u32 v38, 0, v18, v19
	v_or_b32_e32 v18, s24, v179
	v_mul_lo_u32 v18, v18, s52
	v_add_u32_e32 v42, s23, v18
	v_lshlrev_b32_e32 v18, 1, v22
	v_and_b32_e32 v18, 32, v18
	v_add_u32_e32 v18, s25, v18
	v_and_b32_e32 v19, 24, v25
	v_lshlrev_b32_e32 v20, 8, v179
	v_and_b32_e32 v34, 8, v25
	v_and_b32_e32 v35, 56, v25
	s_movk_i32 s4, 0xff
	v_and_b32_e32 v39, 48, v26
	v_mad_u32_u24 v40, v24, s52, 0
	v_lshlrev_b32_e32 v41, 4, v23
	v_lshlrev_b32_e32 v43, 4, v164
	v_and_b32_e32 v44, 0xc0, v26
	v_add3_u32 v45, v18, v19, v20
	v_cmp_gt_u32_e32 vcc, 16, v164
	v_mov_b32_e32 v18, v163
	v_mov_b32_e32 v19, v163
	v_mov_b32_e32 v32, v163
	v_mov_b32_e32 v33, v163
	v_and_b32_e32 v165, 63, v22
	v_cmp_lt_i32_e64 s[4:5], s4, v22
	v_mov_b32_e32 v20, v163
	v_mov_b32_e32 v22, v163
	v_mov_b32_e32 v23, v163
	v_mov_b32_e32 v24, v163
	v_mov_b32_e32 v25, v163
	v_mov_b32_e32 v26, v163
	v_mov_b32_e32 v27, v163
	v_mov_b32_e32 v28, v163
	v_mov_b32_e32 v29, v163
	s_waitcnt vmcnt(8)
; DI void decode_unit(Ctx A_, LAS unsigned char* lds, int b, int h, float lam, int wave, int lane, int tid) {
;     ...
;     bf16x8 qr[4];
;     { const bf16* Qg = P + (rowq + (r & 15)) * PLD + C_QA + h * 128 + mp * 64 + hh * 8;
; #pragma unroll
;       for (int d0 = 0; d0 < 4; ++d0) { const v4u w = *(const v4u*)(Qg + d0 * 16); const v4u z = {0u, 0u, 0u, 0u}; qr[d0] = __builtin_bit_cast(bf16x8, r < 16 ? w : z); } }
;     f32x16 o[4];
; #pragma unroll
;     for (int nb = 0; nb < 4; ++nb)
; #pragma unroll
;         for (int i = 0; i < 16; ++i) o[nb][i] = 0.f;
;     float m = -INFINITY, l = 0.f;
;     const int g16 = (lane >> 4) & 1, p4 = lane & 3, q4 = (lane & 15) >> 2;
	v_cndmask_b32_e32 v129, 0, v9, vcc
	v_cndmask_b32_e32 v125, 0, v5, vcc
	v_cndmask_b32_e32 v124, 0, v4, vcc
	v_cndmask_b32_e32 v123, 0, v3, vcc
	v_cndmask_b32_e32 v122, 0, v2, vcc
	v_cndmask_b32_e32 v128, 0, v8, vcc
	v_cndmask_b32_e32 v127, 0, v7, vcc
	v_cndmask_b32_e32 v126, 0, v6, vcc
	s_waitcnt vmcnt(6)
	v_cndmask_b32_e32 v137, 0, v13, vcc
	v_cndmask_b32_e32 v136, 0, v12, vcc
	v_cndmask_b32_e32 v135, 0, v11, vcc
	v_cndmask_b32_e32 v134, 0, v10, vcc
	s_waitcnt vmcnt(4)
	v_cndmask_b32_e32 v145, 0, v17, vcc
	v_cndmask_b32_e32 v144, 0, v16, vcc
	v_cndmask_b32_e32 v143, 0, v15, vcc
	v_cndmask_b32_e32 v142, 0, v14, vcc
	v_mov_b32_e32 v30, v163
	v_mov_b32_e32 v31, v163
	v_add_u32_e32 v183, v38, v39
	v_add_u32_e32 v184, v40, v41
	v_add_u32_e32 v185, v36, v34
	v_add_u32_e32 v186, v37, v35
	v_add_u32_e32 v187, v42, v43
	v_add_u32_e32 v188, v45, v44
	v_mov_b64_e32 v[64:65], v[32:33]
	v_mov_b64_e32 v[48:49], v[32:33]
	v_mov_b64_e32 v[2:3], v[18:19]
	s_mov_b32 s62, 0
	v_cmp_gt_u32_e64 s[8:9], 32, v165
	v_add_u32_e32 v181, s22, v180
	v_mov_b32_e32 v182, 0
	v_mov_b32_e32 v189, 0xff800000
	s_mov_b64 s[16:17], 0
	v_mov_b64_e32 v[62:63], v[30:31]
	v_mov_b64_e32 v[60:61], v[28:29]
	v_mov_b64_e32 v[58:59], v[26:27]
	v_mov_b64_e32 v[56:57], v[24:25]
	v_mov_b64_e32 v[54:55], v[22:23]
	v_mov_b64_e32 v[52:53], v[20:21]
	v_mov_b64_e32 v[50:51], v[18:19]
	v_mov_b64_e32 v[46:47], v[30:31]
	v_mov_b64_e32 v[44:45], v[28:29]
	v_mov_b64_e32 v[42:43], v[26:27]
	v_mov_b64_e32 v[40:41], v[24:25]
	v_mov_b64_e32 v[38:39], v[22:23]
	v_mov_b64_e32 v[36:37], v[20:21]
	v_mov_b64_e32 v[34:35], v[18:19]
	v_mov_b64_e32 v[4:5], v[20:21]
	v_mov_b64_e32 v[6:7], v[22:23]
	v_mov_b64_e32 v[8:9], v[24:25]
	v_mov_b64_e32 v[10:11], v[26:27]
	v_mov_b64_e32 v[12:13], v[28:29]
	v_mov_b64_e32 v[14:15], v[30:31]
	v_mov_b64_e32 v[16:17], v[32:33]
	v_readlane_b32 s65, v254, 3
	v_readlane_b32 s66, v254, 4
	v_readlane_b32 s67, v254, 5
	v_readlane_b32 s72, v254, 10
	v_readlane_b32 s73, v254, 11
	v_readlane_b32 s74, v254, 12
	v_readlane_b32 s75, v254, 13
	v_readlane_b32 s76, v254, 14
	v_readlane_b32 s77, v254, 15
	v_readlane_b32 s78, v254, 16
	v_readlane_b32 s79, v254, 17

; DI float bf2f(unsigned short u) { return __uint_as_float((unsigned)u << 16); }
; DI unsigned f2bf(float f) { unsigned u = __float_as_uint(f); return (u + 0x7fffu + ((u >> 16) & 1u)) >> 16; }
; DI int crow(int i, int hh) { return (i & 3) + 8 * (i >> 2) + 4 * hh; }
; DI void decode_unit(Ctx A_, LAS unsigned char* lds, int b, int h, float lam, int wave, int lane, int tid) {
;     ...
;         for (int nb = 0; nb < 4; ++nb) { const float sn = SUB_NORM[nb * 32 + r_e];
; #pragma unroll
;             for (int i = 0; i < 8; ++i) { const size_t rw = rowq + crow(i, hh); Y_[rw * YLD + C_YA + h * 128 + nb * 32 + r_e] = (bf16)f2bf(acc[nb][i] * ssq[i] * sn * bf2f(P[rw * PLD + C_ZA + h * 128 + nb * 32 + r_e])); } }
.LBB0_848:
	v_readfirstlane_b32 s98, v0
	s_cmpk_gt_u32 s98, 63
	s_cbranch_scc1 .Ldec_touch_skip
	s_lshr_b32 s98, s101, 3
	s_lshl_b32 s98, s98, 4
	s_add_u32 s98, s98, 0x8000
	s_mul_hi_u32 s99, s98, 0x5800
	s_mul_i32 s98, s98, 0x5800
	v_readlane_b32 s100, v255, 9
	v_and_b32_e32 v206, 63, v0
	s_add_u32 s98, s98, s100
	v_readlane_b32 s100, v255, 10
	v_lshrrev_b32_e32 v207, 1, v206
	s_addc_u32 s99, s99, s100
	s_and_b32 s100, s101, 7
	s_lshl_b32 s100, s100, 8
	s_addk_i32 s100, 0x1800
	s_add_u32 s98, s98, s100
	s_addc_u32 s99, s99, 0
	v_mul_u32_u24_e32 v207, 0x5800, v207
	v_and_b32_e32 v206, 1, v206
	v_lshl_or_b32 v206, v206, 7, v207
	s_nop 0
	global_load_dword v207, v206, s[98:99]
